# attention full-tile fast path: software-pipelined QK/softmax/PV in one wave (8-deep LDS fragment ring), deterministic ssq atomics
# speedup vs baseline: 1.0431x; 1.0332x over previous
; #define G3_LDA(buf, kt, i) __builtin_amdgcn_global_load_lds((const unsigned*)(ga + (size_t)((i) * 64) * lda + (kt) * 64), (lds_u32*)(sdst + (buf) * STAGE + (i) * 8192), 16, 0, 0)
; #define G3_LDB(buf, kt, i) __builtin_amdgcn_global_load_lds((const unsigned*)(gb + (size_t)((i) * 64) * ldb + (kt) * 64), (lds_u32*)(sdst + (buf) * STAGE + B_OFF + (i) * 8192), 16, 0, 0)
; DI void gemm3_mainloop(const int wave8, const int lane, const bf16_t* __restrict__ A, int lda, const bf16_t* __restrict__ Bt, int ldb, int K,
;                        unsigned char* smem, f32x4 (&acc)[8][4]) {
;     ...
;     const int sw = (fr >> 1) & 7;
;     ...
;     asm volatile("s_waitcnt vmcnt(0)" ::: "memory");
;     G3_LDA(0, 0, 0); G3_LDA(0, 0, 1); G3_LDA(0, 0, 2); G3_LDA(0, 0, 3); G3_LDB(0, 0, 0); G3_LDB(0, 0, 1); G3_LDB(0, 0, 2); G3_LDB(0, 0, 3);
;     asm volatile("s_waitcnt vmcnt(0)" ::: "memory");
;     __builtin_amdgcn_s_barrier();
;     for (int kt = 0; kt < nk; kt += 2) { G3_STEP(0, 1, kt); G3_STEP(1, 0, kt + 1); }
.LBB0_90:
	ds_read_b128 v[128:131], v148 offset:32768
	ds_read_b128 v[156:159], v148 offset:34816
	ds_read_b128 v[160:163], v148 offset:36864
	ds_read_b128 v[164:167], v148 offset:38912
	ds_read_b128 v[168:171], v149
	ds_read_b128 v[172:175], v149 offset:2048
	ds_read_b128 v[176:179], v149 offset:4096
	ds_read_b128 v[180:183], v149 offset:6144
	ds_read_b128 v[184:187], v149 offset:8192
	ds_read_b128 v[188:191], v149 offset:10240
	ds_read_b128 v[192:195], v149 offset:12288
	ds_read_b128 v[196:199], v149 offset:14336
	s_waitcnt lgkmcnt(0)
	v_mfma_f32_16x16x32_bf16 v[112:115], v[128:131], v[168:171], v[112:115]
	s_mov_b64 s[8:9], 0x19dc5080
	s_mov_b32 m0, s88
	s_add_i32 s18, s6, 1
	v_mfma_f32_16x16x32_bf16 v[124:127], v[156:159], v[168:171], v[124:127]
	s_add_i32 s7, s6, 2
	s_cmp_lt_u32 s6, 30
	v_mfma_f32_16x16x32_bf16 v[120:123], v[160:163], v[168:171], v[120:123]
	v_mfma_f32_16x16x32_bf16 v[116:119], v[164:167], v[168:171], v[116:119]
	v_lshl_add_u64 v[168:169], v[138:139], 0, v[132:133]
	v_lshl_add_u64 v[170:171], v[168:169], 0, s[8:9]
	s_mov_b64 s[8:9], 0x19e07080
	global_load_lds_dwordx4 v[170:171], off
	v_lshl_add_u64 v[170:171], v[168:169], 0, s[8:9]
	s_mov_b32 m0, s92
	s_mov_b64 s[8:9], 0x19e49080
	v_mfma_f32_16x16x32_bf16 v[96:99], v[128:131], v[172:175], v[96:99]
	v_lshl_add_u64 v[138:139], v[138:139], 0, s[34:35]
	v_mfma_f32_16x16x32_bf16 v[108:111], v[156:159], v[172:175], v[108:111]
	v_mfma_f32_16x16x32_bf16 v[104:107], v[160:163], v[172:175], v[104:107]
	v_mfma_f32_16x16x32_bf16 v[100:103], v[164:167], v[172:175], v[100:103]
	global_load_lds_dwordx4 v[170:171], off
	v_lshl_add_u64 v[170:171], v[168:169], 0, s[8:9]
	s_mov_b32 m0, s93
	s_mov_b64 s[8:9], 0x19e8b080
	v_mfma_f32_16x16x32_bf16 v[80:83], v[128:131], v[176:179], v[80:83]
	v_lshl_add_u64 v[168:169], v[168:169], 0, s[8:9]
	s_mov_b64 s[8:9], 0x245080
	v_mfma_f32_16x16x32_bf16 v[92:95], v[156:159], v[176:179], v[92:95]
	v_mfma_f32_16x16x32_bf16 v[88:91], v[160:163], v[176:179], v[88:91]
	v_mfma_f32_16x16x32_bf16 v[84:87], v[164:167], v[176:179], v[84:87]
	global_load_lds_dwordx4 v[170:171], off
	s_mov_b32 m0, s94
	v_mfma_f32_16x16x32_bf16 v[64:67], v[128:131], v[180:183], v[64:67]
	v_mfma_f32_16x16x32_bf16 v[76:79], v[156:159], v[180:183], v[76:79]
	v_mfma_f32_16x16x32_bf16 v[72:75], v[160:163], v[180:183], v[72:75]
	v_mfma_f32_16x16x32_bf16 v[68:71], v[164:167], v[180:183], v[68:71]
	global_load_lds_dwordx4 v[168:169], off
	s_mov_b32 m0, s89
	v_mfma_f32_16x16x32_bf16 v[48:51], v[128:131], v[184:187], v[48:51]
	v_mfma_f32_16x16x32_bf16 v[60:63], v[156:159], v[184:187], v[60:63]
	v_mfma_f32_16x16x32_bf16 v[56:59], v[160:163], v[184:187], v[56:59]
	v_mfma_f32_16x16x32_bf16 v[52:55], v[164:167], v[184:187], v[52:55]
	v_mfma_f32_16x16x32_bf16 v[32:35], v[128:131], v[188:191], v[32:35]
	v_mfma_f32_16x16x32_bf16 v[44:47], v[156:159], v[188:191], v[44:47]
	v_mfma_f32_16x16x32_bf16 v[40:43], v[160:163], v[188:191], v[40:43]
	v_mfma_f32_16x16x32_bf16 v[36:39], v[164:167], v[188:191], v[36:39]
	v_mfma_f32_16x16x32_bf16 v[12:15], v[128:131], v[192:195], v[12:15]
	v_mfma_f32_16x16x32_bf16 v[24:27], v[156:159], v[192:195], v[24:27]
	v_mfma_f32_16x16x32_bf16 v[20:23], v[160:163], v[192:195], v[20:23]
	v_mfma_f32_16x16x32_bf16 v[16:19], v[164:167], v[192:195], v[16:19]
	v_mfma_f32_16x16x32_bf16 v[0:3], v[128:131], v[196:199], v[0:3]
	v_mfma_f32_16x16x32_bf16 v[8:11], v[156:159], v[196:199], v[8:11]
	v_mfma_f32_16x16x32_bf16 v[4:7], v[160:163], v[196:199], v[4:7]
	v_mfma_f32_16x16x32_bf16 v[28:31], v[164:167], v[196:199], v[28:31]
	ds_read_b128 v[128:131], v150 offset:32768
	ds_read_b128 v[156:159], v150 offset:34816
	ds_read_b128 v[160:163], v150 offset:36864
	ds_read_b128 v[164:167], v150 offset:38912
	ds_read_b128 v[168:171], v151
	ds_read_b128 v[172:175], v151 offset:2048
	ds_read_b128 v[176:179], v151 offset:4096
	ds_read_b128 v[180:183], v151 offset:6144
	ds_read_b128 v[184:187], v151 offset:8192
	ds_read_b128 v[188:191], v151 offset:10240
	ds_read_b128 v[192:195], v151 offset:12288
	ds_read_b128 v[196:199], v151 offset:14336
	s_waitcnt lgkmcnt(0)
	v_mfma_f32_16x16x32_bf16 v[112:115], v[128:131], v[168:171], v[112:115]
	v_mfma_f32_16x16x32_bf16 v[124:127], v[156:159], v[168:171], v[124:127]
	v_mfma_f32_16x16x32_bf16 v[120:123], v[160:163], v[168:171], v[120:123]
	v_mfma_f32_16x16x32_bf16 v[116:119], v[164:167], v[168:171], v[116:119]
	v_lshl_add_u64 v[168:169], v[140:141], 0, v[132:133]
	v_lshl_add_u64 v[170:171], v[168:169], 0, s[8:9]
	s_mov_b64 s[8:9], 0x287080
	global_load_lds_dwordx4 v[170:171], off
	v_lshl_add_u64 v[170:171], v[168:169], 0, s[8:9]
	s_mov_b32 m0, s95
	v_mfma_f32_16x16x32_bf16 v[96:99], v[128:131], v[172:175], v[96:99]
	s_cselect_b64 s[8:9], -1, 0
	s_and_b64 vcc, s[8:9], exec
	s_cselect_b32 s6, s7, s18
	v_mfma_f32_16x16x32_bf16 v[108:111], v[156:159], v[172:175], v[108:111]
	s_lshl_b32 s18, s6, 7
	v_lshl_add_u64 v[140:141], v[140:141], 0, s[34:35]
	s_mov_b32 s6, s7
	v_mfma_f32_16x16x32_bf16 v[104:107], v[160:163], v[172:175], v[104:107]
	v_mfma_f32_16x16x32_bf16 v[100:103], v[164:167], v[172:175], v[100:103]
	global_load_lds_dwordx4 v[170:171], off
	v_lshl_add_u64 v[170:171], v[168:169], 0, s[28:29]
	s_mov_b32 m0, s96
	v_mfma_f32_16x16x32_bf16 v[80:83], v[128:131], v[176:179], v[80:83]
	v_lshl_add_u64 v[168:169], v[168:169], 0, s[30:31]
	v_mfma_f32_16x16x32_bf16 v[92:95], v[156:159], v[176:179], v[92:95]
	v_mfma_f32_16x16x32_bf16 v[88:91], v[160:163], v[176:179], v[88:91]
	v_mfma_f32_16x16x32_bf16 v[84:87], v[164:167], v[176:179], v[84:87]
	global_load_lds_dwordx4 v[170:171], off
	s_mov_b32 m0, s97
	v_mfma_f32_16x16x32_bf16 v[64:67], v[128:131], v[180:183], v[64:67]
	v_mfma_f32_16x16x32_bf16 v[76:79], v[156:159], v[180:183], v[76:79]
	v_mfma_f32_16x16x32_bf16 v[72:75], v[160:163], v[180:183], v[72:75]
	v_mfma_f32_16x16x32_bf16 v[68:71], v[164:167], v[180:183], v[68:71]
	global_load_lds_dwordx4 v[168:169], off
	s_waitcnt vmcnt(0)
	v_mfma_f32_16x16x32_bf16 v[48:51], v[128:131], v[184:187], v[48:51]
	s_barrier
; #define G3_LDA(buf, kt, i) __builtin_amdgcn_global_load_lds((const unsigned*)(ga + (size_t)((i) * 64) * lda + (kt) * 64), (lds_u32*)(sdst + (buf) * STAGE + (i) * 8192), 16, 0, 0)
; #define G3_LDB(buf, kt, i) __builtin_amdgcn_global_load_lds((const unsigned*)(gb + (size_t)((i) * 64) * ldb + (kt) * 64), (lds_u32*)(sdst + (buf) * STAGE + B_OFF + (i) * 8192), 16, 0, 0)
; DI void gemm3_mainloop(const int wave8, const int lane, const bf16_t* __restrict__ A, int lda, const bf16_t* __restrict__ Bt, int ldb, int K,
;                        unsigned char* smem, f32x4 (&acc)[8][4]) {
;     ...
;     const int sw = (fr >> 1) & 7;
;     ...
;     asm volatile("s_waitcnt vmcnt(0)" ::: "memory");
;     G3_LDA(0, 0, 0); G3_LDA(0, 0, 1); G3_LDA(0, 0, 2); G3_LDA(0, 0, 3); G3_LDB(0, 0, 0); G3_LDB(0, 0, 1); G3_LDB(0, 0, 2); G3_LDB(0, 0, 3);
;     asm volatile("s_waitcnt vmcnt(0)" ::: "memory");
;     __builtin_amdgcn_s_barrier();
;     for (int kt = 0; kt < nk; kt += 2) { G3_STEP(0, 1, kt); G3_STEP(1, 0, kt + 1); }
	s_mov_b32 m0, s0
	v_mfma_f32_16x16x32_bf16 v[60:63], v[156:159], v[184:187], v[60:63]
	v_mfma_f32_16x16x32_bf16 v[56:59], v[160:163], v[184:187], v[56:59]
	v_mfma_f32_16x16x32_bf16 v[52:55], v[164:167], v[184:187], v[52:55]
	v_mfma_f32_16x16x32_bf16 v[32:35], v[128:131], v[188:191], v[32:35]
	v_mfma_f32_16x16x32_bf16 v[44:47], v[156:159], v[188:191], v[44:47]
	v_mfma_f32_16x16x32_bf16 v[40:43], v[160:163], v[188:191], v[40:43]
	v_mfma_f32_16x16x32_bf16 v[36:39], v[164:167], v[188:191], v[36:39]
	v_mfma_f32_16x16x32_bf16 v[12:15], v[128:131], v[192:195], v[12:15]
	v_mfma_f32_16x16x32_bf16 v[24:27], v[156:159], v[192:195], v[24:27]
	v_mfma_f32_16x16x32_bf16 v[20:23], v[160:163], v[192:195], v[20:23]
	v_mfma_f32_16x16x32_bf16 v[16:19], v[164:167], v[192:195], v[16:19]
	v_mfma_f32_16x16x32_bf16 v[0:3], v[128:131], v[196:199], v[0:3]
	v_mfma_f32_16x16x32_bf16 v[8:11], v[156:159], v[196:199], v[8:11]
	v_mfma_f32_16x16x32_bf16 v[4:7], v[160:163], v[196:199], v[4:7]
	v_mfma_f32_16x16x32_bf16 v[28:31], v[164:167], v[196:199], v[28:31]
	ds_read_b128 v[128:131], v152
	ds_read_b128 v[156:159], v152 offset:2048
	ds_read_b128 v[160:163], v152 offset:4096
	ds_read_b128 v[164:167], v152 offset:6144
	ds_read_b128 v[168:171], v153
	ds_read_b128 v[172:175], v153 offset:2048
	ds_read_b128 v[176:179], v153 offset:4096
	ds_read_b128 v[180:183], v153 offset:6144
	ds_read_b128 v[184:187], v153 offset:8192
	ds_read_b128 v[188:191], v153 offset:10240
	ds_read_b128 v[192:195], v153 offset:12288
	ds_read_b128 v[196:199], v153 offset:14336
	s_waitcnt lgkmcnt(0)
	v_mfma_f32_16x16x32_bf16 v[112:115], v[128:131], v[168:171], v[112:115]
	v_mfma_f32_16x16x32_bf16 v[124:127], v[156:159], v[168:171], v[124:127]
	v_mfma_f32_16x16x32_bf16 v[120:123], v[160:163], v[168:171], v[120:123]
	v_mfma_f32_16x16x32_bf16 v[116:119], v[164:167], v[168:171], v[116:119]
	v_lshl_add_u64 v[168:169], v[134:135], 0, s[18:19]
	global_load_lds_dwordx4 v[168:169], off
	v_lshl_add_u64 v[170:171], v[168:169], 0, s[22:23]
	s_mov_b32 m0, s55
	v_mfma_f32_16x16x32_bf16 v[96:99], v[128:131], v[172:175], v[96:99]
	v_mfma_f32_16x16x32_bf16 v[108:111], v[156:159], v[172:175], v[108:111]
	v_mfma_f32_16x16x32_bf16 v[104:107], v[160:163], v[172:175], v[104:107]
	v_mfma_f32_16x16x32_bf16 v[100:103], v[164:167], v[172:175], v[100:103]
	global_load_lds_dwordx4 v[170:171], off
	v_lshl_add_u64 v[170:171], v[168:169], 0, s[24:25]
	s_mov_b32 m0, s87
	v_mfma_f32_16x16x32_bf16 v[80:83], v[128:131], v[176:179], v[80:83]
	v_lshl_add_u64 v[168:169], v[168:169], 0, s[26:27]
	v_mfma_f32_16x16x32_bf16 v[92:95], v[156:159], v[176:179], v[92:95]
	v_mfma_f32_16x16x32_bf16 v[88:91], v[160:163], v[176:179], v[88:91]
	v_mfma_f32_16x16x32_bf16 v[84:87], v[164:167], v[176:179], v[84:87]
	global_load_lds_dwordx4 v[170:171], off
	s_mov_b32 m0, s69
	v_mfma_f32_16x16x32_bf16 v[64:67], v[128:131], v[180:183], v[64:67]
	v_mfma_f32_16x16x32_bf16 v[76:79], v[156:159], v[180:183], v[76:79]
	v_mfma_f32_16x16x32_bf16 v[72:75], v[160:163], v[180:183], v[72:75]
	v_mfma_f32_16x16x32_bf16 v[68:71], v[164:167], v[180:183], v[68:71]
	global_load_lds_dwordx4 v[168:169], off
	s_mov_b32 m0, s68
	v_mfma_f32_16x16x32_bf16 v[48:51], v[128:131], v[184:187], v[48:51]
	v_mfma_f32_16x16x32_bf16 v[60:63], v[156:159], v[184:187], v[60:63]
	v_mfma_f32_16x16x32_bf16 v[56:59], v[160:163], v[184:187], v[56:59]
	v_mfma_f32_16x16x32_bf16 v[52:55], v[164:167], v[184:187], v[52:55]
	v_mfma_f32_16x16x32_bf16 v[32:35], v[128:131], v[188:191], v[32:35]
	v_mfma_f32_16x16x32_bf16 v[44:47], v[156:159], v[188:191], v[44:47]
	v_mfma_f32_16x16x32_bf16 v[40:43], v[160:163], v[188:191], v[40:43]
	v_mfma_f32_16x16x32_bf16 v[36:39], v[164:167], v[188:191], v[36:39]
	v_mfma_f32_16x16x32_bf16 v[12:15], v[128:131], v[192:195], v[12:15]
	v_mfma_f32_16x16x32_bf16 v[24:27], v[156:159], v[192:195], v[24:27]
	v_mfma_f32_16x16x32_bf16 v[20:23], v[160:163], v[192:195], v[20:23]
	v_mfma_f32_16x16x32_bf16 v[16:19], v[164:167], v[192:195], v[16:19]
	v_mfma_f32_16x16x32_bf16 v[0:3], v[128:131], v[196:199], v[0:3]
	v_mfma_f32_16x16x32_bf16 v[8:11], v[156:159], v[196:199], v[8:11]
	v_mfma_f32_16x16x32_bf16 v[4:7], v[160:163], v[196:199], v[4:7]
	v_mfma_f32_16x16x32_bf16 v[28:31], v[164:167], v[196:199], v[28:31]
	ds_read_b128 v[156:159], v154
	ds_read_b128 v[160:163], v154 offset:2048
	ds_read_b128 v[164:167], v154 offset:4096
	ds_read_b128 v[128:131], v154 offset:6144
	ds_read_b128 v[168:171], v155
	ds_read_b128 v[172:175], v155 offset:2048
	ds_read_b128 v[176:179], v155 offset:4096
	ds_read_b128 v[180:183], v155 offset:6144
	ds_read_b128 v[184:187], v155 offset:8192
	ds_read_b128 v[188:191], v155 offset:10240
	ds_read_b128 v[192:195], v155 offset:12288
	ds_read_b128 v[196:199], v155 offset:14336
	s_waitcnt lgkmcnt(0)
	v_mfma_f32_16x16x32_bf16 v[112:115], v[156:159], v[168:171], v[112:115]
	v_mfma_f32_16x16x32_bf16 v[124:127], v[160:163], v[168:171], v[124:127]
	v_mfma_f32_16x16x32_bf16 v[120:123], v[164:167], v[168:171], v[120:123]
	v_mfma_f32_16x16x32_bf16 v[116:119], v[128:131], v[168:171], v[116:119]
	v_lshl_add_u64 v[168:169], v[136:137], 0, s[18:19]
	global_load_lds_dwordx4 v[168:169], off
	v_lshl_add_u64 v[170:171], v[168:169], 0, s[22:23]
	s_mov_b32 m0, s39
	v_mfma_f32_16x16x32_bf16 v[96:99], v[156:159], v[172:175], v[96:99]
	v_mfma_f32_16x16x32_bf16 v[108:111], v[160:163], v[172:175], v[108:111]
	v_mfma_f32_16x16x32_bf16 v[104:107], v[164:167], v[172:175], v[104:107]
	v_mfma_f32_16x16x32_bf16 v[100:103], v[128:131], v[172:175], v[100:103]
	global_load_lds_dwordx4 v[170:171], off
	v_lshl_add_u64 v[170:171], v[168:169], 0, s[24:25]
	s_mov_b32 m0, s38
	v_mfma_f32_16x16x32_bf16 v[80:83], v[156:159], v[176:179], v[80:83]
	v_lshl_add_u64 v[168:169], v[168:169], 0, s[26:27]
	v_mfma_f32_16x16x32_bf16 v[92:95], v[160:163], v[176:179], v[92:95]
	v_mfma_f32_16x16x32_bf16 v[88:91], v[164:167], v[176:179], v[88:91]
	v_mfma_f32_16x16x32_bf16 v[84:87], v[128:131], v[176:179], v[84:87]
	global_load_lds_dwordx4 v[170:171], off
	s_mov_b32 m0, s1
	v_mfma_f32_16x16x32_bf16 v[64:67], v[156:159], v[180:183], v[64:67]
	v_mfma_f32_16x16x32_bf16 v[76:79], v[160:163], v[180:183], v[76:79]
	v_mfma_f32_16x16x32_bf16 v[72:75], v[164:167], v[180:183], v[72:75]
	v_mfma_f32_16x16x32_bf16 v[68:71], v[128:131], v[180:183], v[68:71]
	global_load_lds_dwordx4 v[168:169], off
	s_waitcnt vmcnt(0)
	v_mfma_f32_16x16x32_bf16 v[48:51], v[156:159], v[184:187], v[48:51]
	s_barrier
; DI unsigned pk2(float a, float b) { f2_t v = {a, b}; bf2_t r = __builtin_convertvector(v, bf2_t); return __builtin_bit_cast(unsigned, r); }
; DI int fresh_tid(const Params& p) { int t = p.wave_u * 64 + (int)__builtin_amdgcn_mbcnt_hi(~0u, __builtin_amdgcn_mbcnt_lo(~0u, 0u)); asm volatile("" : "+v"(t)); return t; }
; DI void phase1(const Params& p, unsigned char* smem) {
;     ...
;     for_tiles3(T_ / 256, NPAD / 256, [&](int mt, int nt) {
;         const int lane = fresh_tid(p) & 63, fr = lane & 15, fq = lane >> 4, wm = p.wave8 >> 2, wn = p.wave8 & 3;
;         f32x4 acc[8][4];
;         gemm3_mainloop(p.wave8, lane, xn + (size_t)mt * 256 * LDK, LDK, wt + (size_t)nt * 256 * LDK, LDK, DM, smem, acc);
;         const int c128 = nt * 2 + (wn >> 1);
;         if (c128 >= 47) return;
;         bf16_t* dst; int ld, c0;
;         if (c128 < 23) { dst = pa; ld = LDPA; c0 = c128 * 128; } else { dst = pb; ld = LDPB; c0 = (c128 - 23) * 128; }
; #pragma unroll
;         for (int i = 0; i < 8; ++i) {
;             const int m = mt * 256 + wm * 128 + i * 16 + fr;
;             float ss = 0.f;
; #pragma unroll
;             for (int j = 0; j < 4; ++j) {
;                 const f32x4 v = acc[i][j];
;                 ss += v.x * v.x + v.y * v.y + v.z * v.z + v.w * v.w;
;                 u32x2 o; o.x = pk2(v.x, v.y); o.y = pk2(v.z, v.w);
;                 *(u32x2*)(dst + (size_t)m * ld + c0 + (wn & 1) * 64 + j * 16 + fq * 4) = o;
;             }
;             if (c128 < 6) {
;                 ss += __shfl_xor(ss, 16); ss += __shfl_xor(ss, 32);
;                 if (fq == 0) atomicAdd(ssq + (c128 < 4 ? 0 : T_) + m, ss);
	v_mfma_f32_16x16x32_bf16 v[60:63], v[160:163], v[184:187], v[60:63]
	v_mfma_f32_16x16x32_bf16 v[56:59], v[164:167], v[184:187], v[56:59]
	v_mfma_f32_16x16x32_bf16 v[52:55], v[128:131], v[184:187], v[52:55]
	v_mfma_f32_16x16x32_bf16 v[32:35], v[156:159], v[188:191], v[32:35]
	v_mfma_f32_16x16x32_bf16 v[44:47], v[160:163], v[188:191], v[44:47]
	v_mfma_f32_16x16x32_bf16 v[40:43], v[164:167], v[188:191], v[40:43]
	v_mfma_f32_16x16x32_bf16 v[36:39], v[128:131], v[188:191], v[36:39]
	v_mfma_f32_16x16x32_bf16 v[12:15], v[156:159], v[192:195], v[12:15]
	v_mfma_f32_16x16x32_bf16 v[24:27], v[160:163], v[192:195], v[24:27]
	v_mfma_f32_16x16x32_bf16 v[20:23], v[164:167], v[192:195], v[20:23]
	v_mfma_f32_16x16x32_bf16 v[16:19], v[128:131], v[192:195], v[16:19]
	v_mfma_f32_16x16x32_bf16 v[0:3], v[156:159], v[196:199], v[0:3]
	v_mfma_f32_16x16x32_bf16 v[8:11], v[160:163], v[196:199], v[8:11]
	v_mfma_f32_16x16x32_bf16 v[4:7], v[164:167], v[196:199], v[4:7]
	v_mfma_f32_16x16x32_bf16 v[28:31], v[128:131], v[196:199], v[28:31]
	s_cbranch_vccnz .LBB0_90
	s_lshl_b32 s5, s5, 1
	s_or_b32 s36, s5, s44
	s_cmp_gt_i32 s36, 46
	s_cbranch_scc1 .LBB0_88
	s_lshl_b32 s5, s36, 7
	s_add_i32 s6, s5, 0xfffff480
	s_cmp_lt_i32 s36, 23
	s_cselect_b32 s6, s5, s6
	s_cselect_b32 s5, s48, 0xddc5000
	s_cselect_b32 s75, s46, 0xc00
	s_add_u32 s8, s72, s5
	s_addc_u32 s9, s73, 0
	s_lshl_b32 s4, s4, 8
	s_add_i32 s4, s4, s54
	s_ashr_i32 s7, s6, 31
	v_and_or_b32 v130, v147, 15, s4
	s_lshl_b64 s[4:5], s[6:7], 1
	s_add_u32 s4, s8, s4
	s_addc_u32 s5, s9, s5
	s_add_u32 s4, s4, s49
	s_addc_u32 s5, s5, 0
	v_lshlrev_b32_e32 v132, 3, v145
	v_lshl_add_u64 v[128:129], s[4:5], 0, v[132:133]
	v_mov_b32_e32 v132, v130
	v_mad_u64_u32 v[130:131], s[4:5], s75, v130, 0
	v_lshl_add_u64 v[130:131], v[130:131], 1, v[128:129]
	v_cvt_pk_bf16_f32 v134, v112, v113
	v_cvt_pk_bf16_f32 v135, v114, v115
	s_cmp_lt_i32 s36, 6
	global_store_dwordx2 v[130:131], v[134:135], off
	v_cvt_pk_bf16_f32 v134, v124, v125
	v_cvt_pk_bf16_f32 v135, v126, v127
	s_cselect_b64 s[6:7], -1, 0
	s_cmp_lt_i32 s36, 4
	global_store_dwordx2 v[130:131], v[134:135], off offset:32
	v_cvt_pk_bf16_f32 v134, v120, v121
	v_cvt_pk_bf16_f32 v135, v122, v123
	s_cselect_b32 s18, 0, 0x8000
	s_cmp_gt_i32 s36, 5
	v_cmp_gt_u32_e64 s[8:9], 16, v146
	global_store_dwordx2 v[130:131], v[134:135], off offset:64
	v_cvt_pk_bf16_f32 v134, v116, v117
	v_cvt_pk_bf16_f32 v135, v118, v119
	global_store_dwordx2 v[130:131], v[134:135], off offset:96
	s_cbranch_scc1 .LBB0_96
	v_mul_f32_e32 v130, v113, v113
	v_mul_f32_e32 v125, v125, v125
	v_fmac_f32_e32 v130, v112, v112
	v_fmac_f32_e32 v125, v124, v124
	v_mul_f32_e32 v121, v121, v121
	v_fmac_f32_e32 v130, v114, v114
	v_fmac_f32_e32 v125, v126, v126
	v_fmac_f32_e32 v121, v120, v120
	v_mul_f32_e32 v117, v117, v117
	v_fmac_f32_e32 v130, v115, v115
	v_fmac_f32_e32 v125, v127, v127
	v_fmac_f32_e32 v121, v122, v122
	v_fmac_f32_e32 v117, v116, v116
	v_add_f32_e32 v124, v130, v125
	v_fmac_f32_e32 v121, v123, v123
	v_fmac_f32_e32 v117, v118, v118
	v_add_f32_e32 v120, v124, v121
	v_fmac_f32_e32 v117, v119, v119
	v_add_f32_e32 v116, v120, v117
	ds_bpermute_b32 v117, v144, v116
	s_waitcnt lgkmcnt(0)
	v_add_f32_e32 v116, v116, v117
	ds_bpermute_b32 v117, v241, v116
	s_and_saveexec_b64 s[4:5], s[8:9]
	s_cbranch_execz .LBB0_95
	s_lshl_b32 s37, s18, 2
	s_add_u32 s76, s12, s37
	s_addc_u32 s77, s13, 0
	s_waitcnt lgkmcnt(0)
	v_add_f32_e32 v118, v116, v117
	v_lshl_add_u64 v[116:117], v[132:133], 2, s[76:77]
	v_add_f32_e32 v118, 0x45400000, v118
	v_subrev_f32_e32 v118, 0x45400000, v118
	global_atomic_add_f32 v[116:117], v118, off

; DI unsigned pk2(float a, float b) { f2_t v = {a, b}; bf2_t r = __builtin_convertvector(v, bf2_t); return __builtin_bit_cast(unsigned, r); }
; DI void phase1(const Params& p, unsigned char* smem) {
;     ...
; #pragma unroll
;         for (int i = 0; i < 8; ++i) {
;             const int m = mt * 256 + wm * 128 + i * 16 + fr;
;             float ss = 0.f;
; #pragma unroll
;             for (int j = 0; j < 4; ++j) {
;                 const f32x4 v = acc[i][j];
;                 ss += v.x * v.x + v.y * v.y + v.z * v.z + v.w * v.w;
;                 u32x2 o; o.x = pk2(v.x, v.y); o.y = pk2(v.z, v.w);
;                 *(u32x2*)(dst + (size_t)m * ld + c0 + (wn & 1) * 64 + j * 16 + fq * 4) = o;
;             }
;             if (c128 < 6) {
;                 ss += __shfl_xor(ss, 16); ss += __shfl_xor(ss, 32);
;                 if (fq == 0) atomicAdd(ssq + (c128 < 4 ? 0 : T_) + m, ss);
;             }
.LBB0_98:
	s_nop 1
	v_or_b32_e32 v112, 16, v132
	v_mad_u64_u32 v[114:115], s[4:5], s75, v112, 0
	v_lshl_add_u64 v[114:115], v[114:115], 1, v[128:129]
	v_cvt_pk_bf16_f32 v118, v96, v97
	v_cvt_pk_bf16_f32 v119, v98, v99
	global_store_dwordx2 v[114:115], v[118:119], off
	v_cvt_pk_bf16_f32 v118, v108, v109
	v_cvt_pk_bf16_f32 v119, v110, v111
	global_store_dwordx2 v[114:115], v[118:119], off offset:32
	v_cvt_pk_bf16_f32 v118, v104, v105
	v_cvt_pk_bf16_f32 v119, v106, v107
	v_cndmask_b32_e64 v113, 0, 1, s[6:7]
	global_store_dwordx2 v[114:115], v[118:119], off offset:64
	v_cvt_pk_bf16_f32 v118, v100, v101
	v_cvt_pk_bf16_f32 v119, v102, v103
	v_cmp_ne_u32_e64 s[4:5], 1, v113
	s_andn2_b64 vcc, exec, s[6:7]
	global_store_dwordx2 v[114:115], v[118:119], off offset:96
	s_cbranch_vccnz .LBB0_102
	v_mul_f32_e32 v113, v97, v97
	v_mul_f32_e32 v109, v109, v109
	v_fmac_f32_e32 v113, v96, v96
	v_fmac_f32_e32 v109, v108, v108
	v_mul_f32_e32 v105, v105, v105
	v_fmac_f32_e32 v113, v98, v98
	v_fmac_f32_e32 v109, v110, v110
	v_fmac_f32_e32 v105, v104, v104
	v_mul_f32_e32 v101, v101, v101
	v_fmac_f32_e32 v113, v99, v99
	v_fmac_f32_e32 v109, v111, v111
	v_fmac_f32_e32 v105, v106, v106
	v_fmac_f32_e32 v101, v100, v100
	v_add_f32_e32 v108, v113, v109
	v_fmac_f32_e32 v105, v107, v107
	v_fmac_f32_e32 v101, v102, v102
	v_add_f32_e32 v104, v108, v105
	v_fmac_f32_e32 v101, v103, v103
	v_add_f32_e32 v100, v104, v101
	ds_bpermute_b32 v101, v144, v100
	s_waitcnt lgkmcnt(0)
	v_add_f32_e32 v100, v100, v101
	ds_bpermute_b32 v101, v241, v100
	s_and_saveexec_b64 s[6:7], s[8:9]
	s_cbranch_execz .LBB0_101
	s_lshl_b32 s76, s18, 2
	s_add_u32 s76, s12, s76
	s_addc_u32 s77, s13, 0
	s_waitcnt lgkmcnt(0)
	v_add_f32_e32 v102, v100, v101
	v_lshl_add_u64 v[100:101], v[132:133], 2, s[76:77]
	v_add_f32_e32 v102, 0x45400000, v102
	v_subrev_f32_e32 v102, 0x45400000, v102
	global_atomic_add_f32 v[100:101], v102, off offset:64

; DI unsigned pk2(float a, float b) { f2_t v = {a, b}; bf2_t r = __builtin_convertvector(v, bf2_t); return __builtin_bit_cast(unsigned, r); }
; DI void phase1(const Params& p, unsigned char* smem) {
;     ...
; #pragma unroll
;         for (int i = 0; i < 8; ++i) {
;             const int m = mt * 256 + wm * 128 + i * 16 + fr;
;             float ss = 0.f;
; #pragma unroll
;             for (int j = 0; j < 4; ++j) {
;                 const f32x4 v = acc[i][j];
;                 ss += v.x * v.x + v.y * v.y + v.z * v.z + v.w * v.w;
;                 u32x2 o; o.x = pk2(v.x, v.y); o.y = pk2(v.z, v.w);
;                 *(u32x2*)(dst + (size_t)m * ld + c0 + (wn & 1) * 64 + j * 16 + fq * 4) = o;
;             }
;             if (c128 < 6) {
;                 ss += __shfl_xor(ss, 16); ss += __shfl_xor(ss, 32);
;                 if (fq == 0) atomicAdd(ssq + (c128 < 4 ? 0 : T_) + m, ss);
;             }
.LBB0_104:
	s_nop 1
	v_or_b32_e32 v96, 32, v132
	v_mad_u64_u32 v[98:99], s[36:37], s75, v96, 0
	v_lshl_add_u64 v[98:99], v[98:99], 1, v[128:129]
	v_cvt_pk_bf16_f32 v100, v80, v81
	s_waitcnt lgkmcnt(0)
	v_cvt_pk_bf16_f32 v101, v82, v83
	global_store_dwordx2 v[98:99], v[100:101], off
	v_cvt_pk_bf16_f32 v100, v92, v93
	v_cvt_pk_bf16_f32 v101, v94, v95
	global_store_dwordx2 v[98:99], v[100:101], off offset:32
	v_cvt_pk_bf16_f32 v100, v88, v89
	v_cvt_pk_bf16_f32 v101, v90, v91
	global_store_dwordx2 v[98:99], v[100:101], off offset:64
	v_cvt_pk_bf16_f32 v100, v84, v85
	v_cvt_pk_bf16_f32 v101, v86, v87
	s_and_b64 vcc, exec, s[4:5]
	global_store_dwordx2 v[98:99], v[100:101], off offset:96
	s_cbranch_vccnz .LBB0_108
	v_mul_f32_e32 v97, v81, v81
	v_mul_f32_e32 v93, v93, v93
	v_fmac_f32_e32 v97, v80, v80
	v_fmac_f32_e32 v93, v92, v92
	v_mul_f32_e32 v89, v89, v89
	v_fmac_f32_e32 v97, v82, v82
	v_fmac_f32_e32 v93, v94, v94
	v_fmac_f32_e32 v89, v88, v88
	v_mul_f32_e32 v85, v85, v85
	v_fmac_f32_e32 v97, v83, v83
	v_fmac_f32_e32 v93, v95, v95
	v_fmac_f32_e32 v89, v90, v90
	v_fmac_f32_e32 v85, v84, v84
	v_add_f32_e32 v92, v97, v93
	v_fmac_f32_e32 v89, v91, v91
	v_fmac_f32_e32 v85, v86, v86
	v_add_f32_e32 v88, v92, v89
	v_fmac_f32_e32 v85, v87, v87
	v_add_f32_e32 v84, v88, v85
	ds_bpermute_b32 v85, v144, v84
	s_waitcnt lgkmcnt(0)
	v_add_f32_e32 v84, v84, v85
	ds_bpermute_b32 v85, v241, v84
	s_and_saveexec_b64 s[36:37], s[8:9]
	s_cbranch_execz .LBB0_107
	s_lshl_b32 s76, s18, 2
	s_add_u32 s76, s12, s76
	s_addc_u32 s77, s13, 0
	s_waitcnt lgkmcnt(0)
	v_add_f32_e32 v86, v84, v85
	v_lshl_add_u64 v[84:85], v[132:133], 2, s[76:77]
	v_add_f32_e32 v86, 0x45400000, v86
	v_subrev_f32_e32 v86, 0x45400000, v86
	global_atomic_add_f32 v[84:85], v86, off offset:128

; DI unsigned pk2(float a, float b) { f2_t v = {a, b}; bf2_t r = __builtin_convertvector(v, bf2_t); return __builtin_bit_cast(unsigned, r); }
; DI void phase1(const Params& p, unsigned char* smem) {
;     ...
; #pragma unroll
;         for (int i = 0; i < 8; ++i) {
;             const int m = mt * 256 + wm * 128 + i * 16 + fr;
;             float ss = 0.f;
; #pragma unroll
;             for (int j = 0; j < 4; ++j) {
;                 const f32x4 v = acc[i][j];
;                 ss += v.x * v.x + v.y * v.y + v.z * v.z + v.w * v.w;
;                 u32x2 o; o.x = pk2(v.x, v.y); o.y = pk2(v.z, v.w);
;                 *(u32x2*)(dst + (size_t)m * ld + c0 + (wn & 1) * 64 + j * 16 + fq * 4) = o;
;             }
;             if (c128 < 6) {
;                 ss += __shfl_xor(ss, 16); ss += __shfl_xor(ss, 32);
;                 if (fq == 0) atomicAdd(ssq + (c128 < 4 ? 0 : T_) + m, ss);
;             }
.LBB0_110:
	s_nop 1
	v_or_b32_e32 v80, 48, v132
	v_mad_u64_u32 v[82:83], s[36:37], s75, v80, 0
	v_lshl_add_u64 v[82:83], v[82:83], 1, v[128:129]
	v_cvt_pk_bf16_f32 v84, v64, v65
	s_waitcnt lgkmcnt(0)
	v_cvt_pk_bf16_f32 v85, v66, v67
	global_store_dwordx2 v[82:83], v[84:85], off
	v_cvt_pk_bf16_f32 v84, v76, v77
	v_cvt_pk_bf16_f32 v85, v78, v79
	global_store_dwordx2 v[82:83], v[84:85], off offset:32
	v_cvt_pk_bf16_f32 v84, v72, v73
	v_cvt_pk_bf16_f32 v85, v74, v75
	global_store_dwordx2 v[82:83], v[84:85], off offset:64
	v_cvt_pk_bf16_f32 v84, v68, v69
	v_cvt_pk_bf16_f32 v85, v70, v71
	s_and_b64 vcc, exec, s[4:5]
	global_store_dwordx2 v[82:83], v[84:85], off offset:96
	s_cbranch_vccnz .LBB0_114
	v_mul_f32_e32 v81, v65, v65
	v_mul_f32_e32 v77, v77, v77
	v_fmac_f32_e32 v81, v64, v64
	v_fmac_f32_e32 v77, v76, v76
	v_mul_f32_e32 v73, v73, v73
	v_fmac_f32_e32 v81, v66, v66
	v_fmac_f32_e32 v77, v78, v78
	v_fmac_f32_e32 v73, v72, v72
	v_mul_f32_e32 v69, v69, v69
	v_fmac_f32_e32 v81, v67, v67
	v_fmac_f32_e32 v77, v79, v79
	v_fmac_f32_e32 v73, v74, v74
	v_fmac_f32_e32 v69, v68, v68
	v_add_f32_e32 v76, v81, v77
	v_fmac_f32_e32 v73, v75, v75
	v_fmac_f32_e32 v69, v70, v70
	v_add_f32_e32 v72, v76, v73
	v_fmac_f32_e32 v69, v71, v71
	v_add_f32_e32 v68, v72, v69
	ds_bpermute_b32 v69, v144, v68
	s_waitcnt lgkmcnt(0)
	v_add_f32_e32 v68, v68, v69
	ds_bpermute_b32 v69, v241, v68
	s_and_saveexec_b64 s[36:37], s[8:9]
	s_cbranch_execz .LBB0_113
	s_lshl_b32 s76, s18, 2
	s_add_u32 s76, s12, s76
	s_addc_u32 s77, s13, 0
	s_waitcnt lgkmcnt(0)
	v_add_f32_e32 v70, v68, v69
	v_lshl_add_u64 v[68:69], v[132:133], 2, s[76:77]
	v_add_f32_e32 v70, 0x45400000, v70
	v_subrev_f32_e32 v70, 0x45400000, v70
	global_atomic_add_f32 v[68:69], v70, off offset:192

; DI unsigned pk2(float a, float b) { f2_t v = {a, b}; bf2_t r = __builtin_convertvector(v, bf2_t); return __builtin_bit_cast(unsigned, r); }
; DI void phase1(const Params& p, unsigned char* smem) {
;     ...
; #pragma unroll
;         for (int i = 0; i < 8; ++i) {
;             const int m = mt * 256 + wm * 128 + i * 16 + fr;
;             float ss = 0.f;
; #pragma unroll
;             for (int j = 0; j < 4; ++j) {
;                 const f32x4 v = acc[i][j];
;                 ss += v.x * v.x + v.y * v.y + v.z * v.z + v.w * v.w;
;                 u32x2 o; o.x = pk2(v.x, v.y); o.y = pk2(v.z, v.w);
;                 *(u32x2*)(dst + (size_t)m * ld + c0 + (wn & 1) * 64 + j * 16 + fq * 4) = o;
;             }
;             if (c128 < 6) {
;                 ss += __shfl_xor(ss, 16); ss += __shfl_xor(ss, 32);
;                 if (fq == 0) atomicAdd(ssq + (c128 < 4 ? 0 : T_) + m, ss);
;             }
.LBB0_116:
	s_nop 1
	v_or_b32_e32 v64, 64, v132
	v_mad_u64_u32 v[66:67], s[36:37], s75, v64, 0
	v_lshl_add_u64 v[66:67], v[66:67], 1, v[128:129]
	v_cvt_pk_bf16_f32 v68, v48, v49
	s_waitcnt lgkmcnt(0)
	v_cvt_pk_bf16_f32 v69, v50, v51
	global_store_dwordx2 v[66:67], v[68:69], off
	v_cvt_pk_bf16_f32 v68, v60, v61
	v_cvt_pk_bf16_f32 v69, v62, v63
	global_store_dwordx2 v[66:67], v[68:69], off offset:32
	v_cvt_pk_bf16_f32 v68, v56, v57
	v_cvt_pk_bf16_f32 v69, v58, v59
	global_store_dwordx2 v[66:67], v[68:69], off offset:64
	v_cvt_pk_bf16_f32 v68, v52, v53
	v_cvt_pk_bf16_f32 v69, v54, v55
	s_and_b64 vcc, exec, s[4:5]
	global_store_dwordx2 v[66:67], v[68:69], off offset:96
	s_cbranch_vccnz .LBB0_120
	v_mul_f32_e32 v65, v49, v49
	v_mul_f32_e32 v61, v61, v61
	v_fmac_f32_e32 v65, v48, v48
	v_fmac_f32_e32 v61, v60, v60
	v_mul_f32_e32 v57, v57, v57
	v_fmac_f32_e32 v65, v50, v50
	v_fmac_f32_e32 v61, v62, v62
	v_fmac_f32_e32 v57, v56, v56
	v_mul_f32_e32 v53, v53, v53
	v_fmac_f32_e32 v65, v51, v51
	v_fmac_f32_e32 v61, v63, v63
	v_fmac_f32_e32 v57, v58, v58
	v_fmac_f32_e32 v53, v52, v52
	v_add_f32_e32 v60, v65, v61
	v_fmac_f32_e32 v57, v59, v59
	v_fmac_f32_e32 v53, v54, v54
	v_add_f32_e32 v56, v60, v57
	v_fmac_f32_e32 v53, v55, v55
	v_add_f32_e32 v52, v56, v53
	ds_bpermute_b32 v53, v144, v52
	s_waitcnt lgkmcnt(0)
	v_add_f32_e32 v52, v52, v53
	ds_bpermute_b32 v53, v241, v52
	s_and_saveexec_b64 s[36:37], s[8:9]
	s_cbranch_execz .LBB0_119
	s_lshl_b32 s76, s18, 2
	s_add_u32 s76, s12, s76
	s_addc_u32 s77, s13, 0
	s_waitcnt lgkmcnt(0)
	v_add_f32_e32 v54, v52, v53
	v_lshl_add_u64 v[52:53], v[132:133], 2, s[76:77]
	v_add_f32_e32 v54, 0x45400000, v54
	v_subrev_f32_e32 v54, 0x45400000, v54
	global_atomic_add_f32 v[52:53], v54, off offset:256

; DI unsigned pk2(float a, float b) { f2_t v = {a, b}; bf2_t r = __builtin_convertvector(v, bf2_t); return __builtin_bit_cast(unsigned, r); }
; DI void phase1(const Params& p, unsigned char* smem) {
;     ...
; #pragma unroll
;         for (int i = 0; i < 8; ++i) {
;             const int m = mt * 256 + wm * 128 + i * 16 + fr;
;             float ss = 0.f;
; #pragma unroll
;             for (int j = 0; j < 4; ++j) {
;                 const f32x4 v = acc[i][j];
;                 ss += v.x * v.x + v.y * v.y + v.z * v.z + v.w * v.w;
;                 u32x2 o; o.x = pk2(v.x, v.y); o.y = pk2(v.z, v.w);
;                 *(u32x2*)(dst + (size_t)m * ld + c0 + (wn & 1) * 64 + j * 16 + fq * 4) = o;
;             }
;             if (c128 < 6) {
;                 ss += __shfl_xor(ss, 16); ss += __shfl_xor(ss, 32);
;                 if (fq == 0) atomicAdd(ssq + (c128 < 4 ? 0 : T_) + m, ss);
;             }
.LBB0_122:
	s_nop 1
	v_or_b32_e32 v48, 0x50, v132
	v_mad_u64_u32 v[50:51], s[36:37], s75, v48, 0
	v_lshl_add_u64 v[50:51], v[50:51], 1, v[128:129]
	v_cvt_pk_bf16_f32 v52, v32, v33
	s_waitcnt lgkmcnt(0)
	v_cvt_pk_bf16_f32 v53, v34, v35
	global_store_dwordx2 v[50:51], v[52:53], off
	v_cvt_pk_bf16_f32 v52, v44, v45
	v_cvt_pk_bf16_f32 v53, v46, v47
	global_store_dwordx2 v[50:51], v[52:53], off offset:32
	v_cvt_pk_bf16_f32 v52, v40, v41
	v_cvt_pk_bf16_f32 v53, v42, v43
	global_store_dwordx2 v[50:51], v[52:53], off offset:64
	v_cvt_pk_bf16_f32 v52, v36, v37
	v_cvt_pk_bf16_f32 v53, v38, v39
	s_and_b64 vcc, exec, s[4:5]
	global_store_dwordx2 v[50:51], v[52:53], off offset:96
	s_cbranch_vccnz .LBB0_126
	v_mul_f32_e32 v49, v33, v33
	v_mul_f32_e32 v45, v45, v45
	v_fmac_f32_e32 v49, v32, v32
	v_fmac_f32_e32 v45, v44, v44
	v_mul_f32_e32 v41, v41, v41
	v_fmac_f32_e32 v49, v34, v34
	v_fmac_f32_e32 v45, v46, v46
	v_fmac_f32_e32 v41, v40, v40
	v_mul_f32_e32 v37, v37, v37
	v_fmac_f32_e32 v49, v35, v35
	v_fmac_f32_e32 v45, v47, v47
	v_fmac_f32_e32 v41, v42, v42
	v_fmac_f32_e32 v37, v36, v36
	v_add_f32_e32 v44, v49, v45
	v_fmac_f32_e32 v41, v43, v43
	v_fmac_f32_e32 v37, v38, v38
	v_add_f32_e32 v40, v44, v41
	v_fmac_f32_e32 v37, v39, v39
	v_add_f32_e32 v36, v40, v37
	ds_bpermute_b32 v37, v144, v36
	s_waitcnt lgkmcnt(0)
	v_add_f32_e32 v36, v36, v37
	ds_bpermute_b32 v37, v241, v36
	s_and_saveexec_b64 s[36:37], s[8:9]
	s_cbranch_execz .LBB0_125
	s_lshl_b32 s76, s18, 2
	s_add_u32 s76, s12, s76
	s_addc_u32 s77, s13, 0
	s_waitcnt lgkmcnt(0)
	v_add_f32_e32 v38, v36, v37
	v_lshl_add_u64 v[36:37], v[132:133], 2, s[76:77]
	v_add_f32_e32 v38, 0x45400000, v38
	v_subrev_f32_e32 v38, 0x45400000, v38
	global_atomic_add_f32 v[36:37], v38, off offset:320

; DI unsigned pk2(float a, float b) { f2_t v = {a, b}; bf2_t r = __builtin_convertvector(v, bf2_t); return __builtin_bit_cast(unsigned, r); }
; DI void phase1(const Params& p, unsigned char* smem) {
;     ...
; #pragma unroll
;         for (int i = 0; i < 8; ++i) {
;             const int m = mt * 256 + wm * 128 + i * 16 + fr;
;             float ss = 0.f;
; #pragma unroll
;             for (int j = 0; j < 4; ++j) {
;                 const f32x4 v = acc[i][j];
;                 ss += v.x * v.x + v.y * v.y + v.z * v.z + v.w * v.w;
;                 u32x2 o; o.x = pk2(v.x, v.y); o.y = pk2(v.z, v.w);
;                 *(u32x2*)(dst + (size_t)m * ld + c0 + (wn & 1) * 64 + j * 16 + fq * 4) = o;
;             }
;             if (c128 < 6) {
;                 ss += __shfl_xor(ss, 16); ss += __shfl_xor(ss, 32);
;                 if (fq == 0) atomicAdd(ssq + (c128 < 4 ? 0 : T_) + m, ss);
;             }
.LBB0_128:
	s_nop 1
	v_or_b32_e32 v32, 0x60, v132
	v_mad_u64_u32 v[34:35], s[36:37], s75, v32, 0
	v_lshl_add_u64 v[34:35], v[34:35], 1, v[128:129]
	v_cvt_pk_bf16_f32 v36, v12, v13
	s_waitcnt lgkmcnt(0)
	v_cvt_pk_bf16_f32 v37, v14, v15
	global_store_dwordx2 v[34:35], v[36:37], off
	v_cvt_pk_bf16_f32 v36, v24, v25
	v_cvt_pk_bf16_f32 v37, v26, v27
	global_store_dwordx2 v[34:35], v[36:37], off offset:32
	v_cvt_pk_bf16_f32 v36, v20, v21
	v_cvt_pk_bf16_f32 v37, v22, v23
	global_store_dwordx2 v[34:35], v[36:37], off offset:64
	v_cvt_pk_bf16_f32 v36, v16, v17
	v_cvt_pk_bf16_f32 v37, v18, v19
	s_and_b64 vcc, exec, s[4:5]
	global_store_dwordx2 v[34:35], v[36:37], off offset:96
	s_cbranch_vccnz .LBB0_132
	v_mul_f32_e32 v33, v13, v13
	v_mul_f32_e32 v25, v25, v25
	v_fmac_f32_e32 v33, v12, v12
	v_fmac_f32_e32 v25, v24, v24
	v_mul_f32_e32 v21, v21, v21
	v_fmac_f32_e32 v33, v14, v14
	v_fmac_f32_e32 v25, v26, v26
	v_fmac_f32_e32 v21, v20, v20
	v_mul_f32_e32 v17, v17, v17
	v_fmac_f32_e32 v33, v15, v15
	v_fmac_f32_e32 v25, v27, v27
	v_fmac_f32_e32 v21, v22, v22
	v_fmac_f32_e32 v17, v16, v16
	v_add_f32_e32 v24, v33, v25
	v_fmac_f32_e32 v21, v23, v23
	v_fmac_f32_e32 v17, v18, v18
	v_add_f32_e32 v20, v24, v21
	v_fmac_f32_e32 v17, v19, v19
	v_add_f32_e32 v16, v20, v17
	ds_bpermute_b32 v17, v144, v16
	s_waitcnt lgkmcnt(0)
	v_add_f32_e32 v16, v16, v17
	ds_bpermute_b32 v17, v241, v16
	s_and_saveexec_b64 s[36:37], s[8:9]
	s_cbranch_execz .LBB0_131
	s_lshl_b32 s76, s18, 2
	s_add_u32 s76, s12, s76
	s_addc_u32 s77, s13, 0
	s_waitcnt lgkmcnt(0)
	v_add_f32_e32 v18, v16, v17
	v_lshl_add_u64 v[16:17], v[132:133], 2, s[76:77]
	v_add_f32_e32 v18, 0x45400000, v18
	v_subrev_f32_e32 v18, 0x45400000, v18
	global_atomic_add_f32 v[16:17], v18, off offset:384

; DI unsigned pk2(float a, float b) { f2_t v = {a, b}; bf2_t r = __builtin_convertvector(v, bf2_t); return __builtin_bit_cast(unsigned, r); }
; DI void phase1(const Params& p, unsigned char* smem) {
;     ...
; #pragma unroll
;         for (int i = 0; i < 8; ++i) {
;             const int m = mt * 256 + wm * 128 + i * 16 + fr;
;             float ss = 0.f;
; #pragma unroll
;             for (int j = 0; j < 4; ++j) {
;                 const f32x4 v = acc[i][j];
;                 ss += v.x * v.x + v.y * v.y + v.z * v.z + v.w * v.w;
;                 u32x2 o; o.x = pk2(v.x, v.y); o.y = pk2(v.z, v.w);
;                 *(u32x2*)(dst + (size_t)m * ld + c0 + (wn & 1) * 64 + j * 16 + fq * 4) = o;
;             }
;             if (c128 < 6) {
;                 ss += __shfl_xor(ss, 16); ss += __shfl_xor(ss, 32);
;                 if (fq == 0) atomicAdd(ssq + (c128 < 4 ? 0 : T_) + m, ss);
;             }
.LBB0_134:
	s_nop 1
	v_or_b32_e32 v12, 0x70, v132
	v_mad_u64_u32 v[14:15], s[36:37], s75, v12, 0
	v_lshl_add_u64 v[14:15], v[14:15], 1, v[128:129]
	v_cvt_pk_bf16_f32 v16, v0, v1
	s_waitcnt lgkmcnt(0)
	v_cvt_pk_bf16_f32 v17, v2, v3
	global_store_dwordx2 v[14:15], v[16:17], off
	v_cvt_pk_bf16_f32 v16, v8, v9
	v_cvt_pk_bf16_f32 v17, v10, v11
	global_store_dwordx2 v[14:15], v[16:17], off offset:32
	v_cvt_pk_bf16_f32 v16, v4, v5
	v_cvt_pk_bf16_f32 v17, v6, v7
	global_store_dwordx2 v[14:15], v[16:17], off offset:64
	v_cvt_pk_bf16_f32 v16, v28, v29
	v_cvt_pk_bf16_f32 v17, v30, v31
	s_and_b64 vcc, exec, s[4:5]
	global_store_dwordx2 v[14:15], v[16:17], off offset:96
	s_cbranch_vccnz .LBB0_138
	v_mul_f32_e32 v13, v1, v1
	v_mul_f32_e32 v9, v9, v9
	v_fmac_f32_e32 v13, v0, v0
	v_fmac_f32_e32 v9, v8, v8
	v_mul_f32_e32 v5, v5, v5
	v_fmac_f32_e32 v13, v2, v2
	v_fmac_f32_e32 v9, v10, v10
	v_fmac_f32_e32 v5, v4, v4
	v_fmac_f32_e32 v13, v3, v3
	v_fmac_f32_e32 v9, v11, v11
	v_fmac_f32_e32 v5, v6, v6
	v_add_f32_e32 v8, v13, v9
	v_fmac_f32_e32 v5, v7, v7
	v_add_f32_e32 v4, v8, v5
	v_mul_f32_e32 v5, v29, v29
	v_fmac_f32_e32 v5, v28, v28
	v_fmac_f32_e32 v5, v30, v30
	v_fmac_f32_e32 v5, v31, v31
	v_add_f32_e32 v4, v4, v5
	ds_bpermute_b32 v5, v144, v4
	s_waitcnt lgkmcnt(0)
	v_add_f32_e32 v4, v4, v5
	ds_bpermute_b32 v5, v241, v4
	s_and_saveexec_b64 s[4:5], s[8:9]
	s_cbranch_execz .LBB0_137
	s_lshl_b32 s8, s18, 2
	s_add_u32 s8, s12, s8
	s_addc_u32 s9, s13, 0
	s_waitcnt lgkmcnt(0)
	v_add_f32_e32 v6, v4, v5
	v_lshl_add_u64 v[4:5], v[132:133], 2, s[8:9]
	v_add_f32_e32 v6, 0x45400000, v6
	v_subrev_f32_e32 v6, 0x45400000, v6
	global_atomic_add_f32 v[4:5], v6, off offset:448

; #define MFMA(a, b, c) __builtin_amdgcn_mfma_f32_32x32x16_bf16((a), (b), (c), 0, 0, 0)
; DI int crow(int e, int h) { return (e & 3) + 8 * (e >> 2) + 4 * h; }
; DI void attn_item(const Params& p, int bh, int qb, unsigned char* smem) {
;     ...
;     for (int jt = 0; jt < ntiles; ++jt) {
;         if (jt + 1 < ntiles) KV_STORE((jt + 1) & 1);
;         if (jt + 2 < ntiles) KV_LOAD(jt + 2);
; #pragma unroll
;         for (int mt = 0; mt < 2; ++mt) {
;         const int key0 = jt * 64 + mt * 32;
;         if (key0 <= wrow0) {
;             const bf16_t* sK = sbase + (jt & 1) * STG + mt * 32 * 200; const bf16_t* sV = sbase + (jt & 1) * STG + KST + mt * 32;
;             f32x16 sc; zero_acc(sc);
;             {
;                 bf16x8 kf[12];
; #pragma unroll
;                 for (int ks = 0; ks < 12; ++ks) kf[ks] = *(const bf16x8*)(sK + r * 200 + ks * 16 + h * 8);
; #pragma unroll
;                 for (int ks = 0; ks < 12; ++ks) sc = MFMA(kf[ks], qf[ks], sc);
;                 __builtin_amdgcn_sched_group_barrier(0x100, 6, 0);
; #pragma unroll
;                 for (int q = 0; q < 6; ++q) { __builtin_amdgcn_sched_group_barrier(0x008, 1, 0); __builtin_amdgcn_sched_group_barrier(0x100, 1, 0); }
;                 __builtin_amdgcn_sched_group_barrier(0x008, 6, 0);
;             }
;             if (key0 == wrow0) {
; #pragma unroll
;                 for (int e = 0; e < 16; ++e) if (key0 + crow(e, h) > qrow) sc[e] = -INFINITY;
;             }
.LBB0_460:
	s_add_i32 s75, s64, s44
	s_add_i32 s76, s44, 0xffffff80
	s_bitcmp1_b32 s74, 0
	s_cselect_b32 s77, 0xac00, 0
	s_add_i32 s77, s77, 0
	v_add_u32_e32 v64, s77, v182
	v_add_u32_e32 v183, s77, v178
	s_add_i32 s99, s76, 64
	s_cmp_le_i32 s99, s62
	s_cbranch_scc1 .Lattn_fast
	s_cmp_gt_i32 s76, s62
	v_add_u32_e32 v184, v64, v148
	s_cbranch_scc1 .LBB0_464
	ds_read_b128 v[64:67], v184
	ds_read_b128 v[186:189], v184 offset:32
	ds_read_b128 v[190:193], v184 offset:64
	ds_read_b128 v[194:197], v184 offset:96
	ds_read_b128 v[198:201], v184 offset:128
	ds_read_b128 v[202:205], v184 offset:160
	s_cmpk_lg_i32 s75, 0x1f80
	s_waitcnt lgkmcnt(5)
	v_mfma_f32_32x32x16_bf16 v[64:79], v[64:67], v[80:83], 0
	ds_read_b128 v[206:209], v184 offset:192
	s_waitcnt lgkmcnt(5)
	v_mfma_f32_32x32x16_bf16 v[64:79], v[186:189], v[84:87], v[64:79]
	ds_read_b128 v[186:189], v184 offset:224
	s_waitcnt lgkmcnt(5)
	v_mfma_f32_32x32x16_bf16 v[64:79], v[190:193], v[88:91], v[64:79]
	ds_read_b128 v[190:193], v184 offset:256
	s_waitcnt lgkmcnt(5)
	v_mfma_f32_32x32x16_bf16 v[64:79], v[194:197], v[92:95], v[64:79]
	ds_read_b128 v[194:197], v184 offset:288
	s_waitcnt lgkmcnt(5)
	v_mfma_f32_32x32x16_bf16 v[64:79], v[198:201], v[96:99], v[64:79]
	ds_read_b128 v[198:201], v184 offset:320
	s_waitcnt lgkmcnt(5)
	v_mfma_f32_32x32x16_bf16 v[64:79], v[202:205], v[100:103], v[64:79]
	ds_read_b128 v[202:205], v184 offset:352
	s_waitcnt lgkmcnt(5)
	v_mfma_f32_32x32x16_bf16 v[64:79], v[206:209], v[104:107], v[64:79]
	s_waitcnt lgkmcnt(4)
	v_mfma_f32_32x32x16_bf16 v[64:79], v[186:189], v[108:111], v[64:79]
	s_waitcnt lgkmcnt(3)
	v_mfma_f32_32x32x16_bf16 v[64:79], v[190:193], v[112:115], v[64:79]
	s_waitcnt lgkmcnt(2)
	v_mfma_f32_32x32x16_bf16 v[64:79], v[194:197], v[116:119], v[64:79]
	s_waitcnt lgkmcnt(1)
	v_mfma_f32_32x32x16_bf16 v[64:79], v[198:201], v[120:123], v[64:79]
	s_waitcnt lgkmcnt(0)
	v_mfma_f32_32x32x16_bf16 v[64:79], v[202:205], v[124:127], v[64:79]
	s_cbranch_scc1 .LBB0_463
	s_nop 10
	v_cndmask_b32_e32 v185, v64, v163, vcc
	v_cndmask_b32_e64 v65, v163, v65, s[6:7]
	v_cndmask_b32_e64 v64, v185, v64, s[6:7]
	v_cndmask_b32_e64 v66, v66, v163, s[8:9]
	v_cndmask_b32_e64 v67, v67, v163, s[10:11]
	v_cndmask_b32_e64 v68, v68, v163, s[12:13]
	v_cndmask_b32_e64 v69, v69, v163, s[14:15]
	v_cndmask_b32_e64 v70, v70, v163, s[16:17]
	v_cndmask_b32_e64 v71, v71, v163, s[18:19]
	v_cndmask_b32_e64 v72, v72, v163, s[20:21]
	v_cndmask_b32_e64 v73, v73, v163, s[22:23]
	v_cndmask_b32_e64 v74, v74, v163, s[24:25]
	v_cndmask_b32_e64 v75, v75, v163, s[26:27]
	v_cndmask_b32_e64 v76, v76, v163, s[28:29]
	v_cndmask_b32_e64 v77, v77, v163, s[30:31]
	v_cndmask_b32_e64 v78, v78, v163, s[34:35]
	v_cndmask_b32_e64 v79, v79, v163, s[36:37]

; DI void attn_item(const Params& p, int bh, int qb, unsigned char* smem) {
;     ...
;         for (int mt = 0; mt < 2; ++mt) {
;         const int key0 = jt * 64 + mt * 32;
;         if (key0 <= wrow0) {
;             const bf16_t* sK = sbase + (jt & 1) * STG + mt * 32 * 200; const bf16_t* sV = sbase + (jt & 1) * STG + KST + mt * 32;
;             f32x16 sc; zero_acc(sc);
;             {
;                 bf16x8 kf[12];
; #pragma unroll
;                 for (int ks = 0; ks < 12; ++ks) kf[ks] = *(const bf16x8*)(sK + r * 200 + ks * 16 + h * 8);
; #pragma unroll
;                 for (int ks = 0; ks < 12; ++ks) sc = MFMA(kf[ks], qf[ks], sc);
;                 __builtin_amdgcn_sched_group_barrier(0x100, 6, 0);
; #pragma unroll
;                 for (int q = 0; q < 6; ++q) { __builtin_amdgcn_sched_group_barrier(0x008, 1, 0); __builtin_amdgcn_sched_group_barrier(0x100, 1, 0); }
;                 __builtin_amdgcn_sched_group_barrier(0x008, 6, 0);
;             }
;             if (key0 == wrow0) {
; #pragma unroll
;                 for (int e = 0; e < 16; ++e) if (key0 + crow(e, h) > qrow) sc[e] = -INFINITY;
;             }
;             if (jt == 0 && mt == 0) {
;                 float mx = sc[0];
; #pragma unroll
;                 for (int e = 1; e < 16; ++e) mx = fmaxf(mx, sc[e]);
;                 m_run = fmaxf(mx, __shfl_xor(mx, 32));
;             }
;             float ls = 0.f;
; #pragma unroll
;             for (int e = 0; e < 16; ++e) { const float pv = __builtin_amdgcn_exp2f(sc[e] - m_run); sc[e] = pv; ls += pv; }
;             l_run += ls;
;             bf16x8 pf[2]; pf[0] = pack8<0>(sc); pf[1] = pack8<1>(sc);
;             {
;                 bf16x8 vfr[2][4];
; #pragma unroll
;                 for (int s = 0; s < 2; ++s)
; #pragma unroll
;                     for (int t = 0; t < 4; ++t) vfr[s][t] = ld_frag_perm(sV + (t * 32 + r) * 72 + 16 * s + 4 * h);
; #pragma unroll
;                 for (int s = 0; s < 2; ++s)
; #pragma unroll
;                     for (int t = 0; t < 4; ++t) O[t] = MFMA(vfr[s][t], pf[s], O[t]);
;                 __builtin_amdgcn_sched_group_barrier(0x100, 8, 0);
; #pragma unroll
;                 for (int q = 0; q < 4; ++q) { __builtin_amdgcn_sched_group_barrier(0x008, 1, 0); __builtin_amdgcn_sched_group_barrier(0x100, 2, 0); }
;                 __builtin_amdgcn_sched_group_barrier(0x008, 4, 0);
;             }
.Lattn_fast:
	v_add_u32_e32 v184, v64, v148
	v_add_u32_e32 v185, v183, v181
	ds_read_b128 v[204:207], v184 offset:0
	ds_read_b128 v[208:211], v184 offset:32
	ds_read_b128 v[212:215], v184 offset:64
	ds_read_b128 v[216:219], v184 offset:96
	ds_read_b128 v[220:223], v184 offset:128
	ds_read_b128 v[228:231], v184 offset:160
	ds_read_b128 v[232:235], v184 offset:192
	ds_read_b128 v[242:245], v184 offset:224
	v_mov_b32_e32 v224, 0
	v_mov_b32_e32 v225, 0
	v_mov_b32_e32 v226, 0
	v_mov_b32_e32 v183, 0
	s_waitcnt lgkmcnt(7)
	v_mfma_f32_32x32x16_bf16 v[64:79], v[204:207], v[80:83], 0
	ds_read_b128 v[204:207], v184 offset:256
	s_waitcnt lgkmcnt(7)
	v_mfma_f32_32x32x16_bf16 v[64:79], v[208:211], v[84:87], v[64:79]
	ds_read_b128 v[208:211], v184 offset:288
	s_waitcnt lgkmcnt(7)
	v_mfma_f32_32x32x16_bf16 v[64:79], v[212:215], v[88:91], v[64:79]
	ds_read_b128 v[212:215], v184 offset:320
	s_waitcnt lgkmcnt(7)
	v_mfma_f32_32x32x16_bf16 v[64:79], v[216:219], v[92:95], v[64:79]
	ds_read_b128 v[216:219], v184 offset:352
	s_waitcnt lgkmcnt(7)
	v_mfma_f32_32x32x16_bf16 v[64:79], v[220:223], v[96:99], v[64:79]
	ds_read_b128 v[220:223], v184 offset:12800
	s_waitcnt lgkmcnt(7)
	v_mfma_f32_32x32x16_bf16 v[64:79], v[228:231], v[100:103], v[64:79]
	ds_read_b128 v[228:231], v184 offset:12832
	s_waitcnt lgkmcnt(7)
	v_mfma_f32_32x32x16_bf16 v[64:79], v[232:235], v[104:107], v[64:79]
	ds_read_b128 v[232:235], v184 offset:12864
	s_waitcnt lgkmcnt(7)
	v_mfma_f32_32x32x16_bf16 v[64:79], v[242:245], v[108:111], v[64:79]
	ds_read_b128 v[242:245], v184 offset:12896
	s_waitcnt lgkmcnt(7)
	v_mfma_f32_32x32x16_bf16 v[64:79], v[204:207], v[112:115], v[64:79]
	ds_read_b128 v[204:207], v184 offset:12928
	s_waitcnt lgkmcnt(7)
	v_mfma_f32_32x32x16_bf16 v[64:79], v[208:211], v[116:119], v[64:79]
	ds_read_b128 v[208:211], v184 offset:12960
	s_waitcnt lgkmcnt(7)
	v_mfma_f32_32x32x16_bf16 v[64:79], v[212:215], v[120:123], v[64:79]
	ds_read_b128 v[212:215], v184 offset:12992
	s_waitcnt lgkmcnt(7)
	v_mfma_f32_32x32x16_bf16 v[64:79], v[216:219], v[124:127], v[64:79]
	ds_read_b128 v[216:219], v184 offset:13024
	s_waitcnt lgkmcnt(7)
	v_mfma_f32_32x32x16_bf16 v[188:203], v[220:223], v[80:83], 0
	ds_read_b128 v[220:223], v184 offset:13056
	s_waitcnt lgkmcnt(7)
	v_mfma_f32_32x32x16_bf16 v[188:203], v[228:231], v[84:87], v[188:203]
	ds_read_b128 v[228:231], v184 offset:13088
	s_waitcnt lgkmcnt(7)
	v_mfma_f32_32x32x16_bf16 v[188:203], v[232:235], v[88:91], v[188:203]
	ds_read_b128 v[232:235], v184 offset:13120
	s_nop 1
	v_sub_f32_e32 v186, v64, v179
	v_exp_f32_e32 v64, v186
	v_sub_f32_e32 v187, v65, v179
	v_exp_f32_e32 v65, v187
	v_sub_f32_e32 v186, v66, v179
	v_exp_f32_e32 v66, v186
	s_waitcnt lgkmcnt(7)
	v_mfma_f32_32x32x16_bf16 v[188:203], v[242:245], v[92:95], v[188:203]
	ds_read_b128 v[242:245], v184 offset:13152
	v_add_f32_e32 v224, v64, v224
	v_sub_f32_e32 v187, v67, v179
	v_exp_f32_e32 v67, v187
	v_add_f32_e32 v225, v65, v225
	v_sub_f32_e32 v186, v68, v179
	v_exp_f32_e32 v68, v186
	s_waitcnt lgkmcnt(7)
	v_mfma_f32_32x32x16_bf16 v[188:203], v[204:207], v[96:99], v[188:203]
	ds_read_b64 v[204:205], v185 offset:25600
	ds_read_b64 v[206:207], v185 offset:25616
	v_add_f32_e32 v224, v66, v224
	v_sub_f32_e32 v187, v69, v179
	v_exp_f32_e32 v69, v187
	v_add_f32_e32 v225, v67, v225
	v_sub_f32_e32 v186, v70, v179
	v_exp_f32_e32 v70, v186
	s_waitcnt lgkmcnt(8)
	v_mfma_f32_32x32x16_bf16 v[188:203], v[208:211], v[100:103], v[188:203]
	ds_read_b64 v[208:209], v185 offset:30208
	ds_read_b64 v[210:211], v185 offset:30224
	v_add_f32_e32 v224, v68, v224
	v_sub_f32_e32 v187, v71, v179
	v_exp_f32_e32 v71, v187
	v_add_f32_e32 v225, v69, v225
	v_add_f32_e32 v224, v70, v224
	v_add_f32_e32 v225, v71, v225
	s_waitcnt lgkmcnt(9)
	v_mfma_f32_32x32x16_bf16 v[188:203], v[212:215], v[104:107], v[188:203]
	ds_read_b64 v[212:213], v185 offset:34816
	ds_read_b64 v[214:215], v185 offset:34832
	v_cvt_pk_bf16_f32 v64, v64, v65
	v_cvt_pk_bf16_f32 v65, v66, v67
	v_cvt_pk_bf16_f32 v66, v68, v69
	v_cvt_pk_bf16_f32 v67, v70, v71
	s_waitcnt lgkmcnt(10)
	v_mfma_f32_32x32x16_bf16 v[188:203], v[216:219], v[108:111], v[188:203]
	ds_read_b64 v[216:217], v185 offset:39424
	ds_read_b64 v[218:219], v185 offset:39440
	v_sub_f32_e32 v186, v72, v179
	v_exp_f32_e32 v72, v186
	v_sub_f32_e32 v187, v73, v179
	v_exp_f32_e32 v73, v187
	v_sub_f32_e32 v186, v74, v179
	v_exp_f32_e32 v74, v186
	s_waitcnt lgkmcnt(11)
	v_mfma_f32_32x32x16_bf16 v[188:203], v[220:223], v[112:115], v[188:203]
	ds_read_b64 v[220:221], v185 offset:25632
	ds_read_b64 v[222:223], v185 offset:25648
	v_add_f32_e32 v224, v72, v224
	v_sub_f32_e32 v187, v75, v179
	v_exp_f32_e32 v75, v187
	v_add_f32_e32 v225, v73, v225
	v_sub_f32_e32 v186, v76, v179
	v_exp_f32_e32 v76, v186
	s_waitcnt lgkmcnt(12)
; #define MFMA(a, b, c) __builtin_amdgcn_mfma_f32_32x32x16_bf16((a), (b), (c), 0, 0, 0)
; DI void attn_item(const Params& p, int bh, int qb, unsigned char* smem) {
;     ...
;             float ls = 0.f;
; #pragma unroll
;             for (int e = 0; e < 16; ++e) { const float pv = __builtin_amdgcn_exp2f(sc[e] - m_run); sc[e] = pv; ls += pv; }
;             l_run += ls;
;             bf16x8 pf[2]; pf[0] = pack8<0>(sc); pf[1] = pack8<1>(sc);
;             {
;                 bf16x8 vfr[2][4];
; #pragma unroll
;                 for (int s = 0; s < 2; ++s)
; #pragma unroll
;                     for (int t = 0; t < 4; ++t) vfr[s][t] = ld_frag_perm(sV + (t * 32 + r) * 72 + 16 * s + 4 * h);
; #pragma unroll
;                 for (int s = 0; s < 2; ++s)
; #pragma unroll
;                     for (int t = 0; t < 4; ++t) O[t] = MFMA(vfr[s][t], pf[s], O[t]);
;                 __builtin_amdgcn_sched_group_barrier(0x100, 8, 0);
; #pragma unroll
;                 for (int q = 0; q < 4; ++q) { __builtin_amdgcn_sched_group_barrier(0x008, 1, 0); __builtin_amdgcn_sched_group_barrier(0x100, 2, 0); }
;                 __builtin_amdgcn_sched_group_barrier(0x008, 4, 0);
;             }
	v_mfma_f32_32x32x16_bf16 v[188:203], v[228:231], v[116:119], v[188:203]
	ds_read_b64 v[228:229], v185 offset:30240
	ds_read_b64 v[230:231], v185 offset:30256
	v_add_f32_e32 v224, v74, v224
	v_sub_f32_e32 v187, v77, v179
	v_exp_f32_e32 v77, v187
	v_add_f32_e32 v225, v75, v225
	v_sub_f32_e32 v186, v78, v179
	v_exp_f32_e32 v78, v186
	s_waitcnt lgkmcnt(13)
	v_mfma_f32_32x32x16_bf16 v[188:203], v[232:235], v[120:123], v[188:203]
	ds_read_b64 v[232:233], v185 offset:34848
	ds_read_b64 v[234:235], v185 offset:34864
	v_add_f32_e32 v224, v76, v224
	v_sub_f32_e32 v187, v79, v179
	v_exp_f32_e32 v79, v187
	v_add_f32_e32 v225, v77, v225
	v_add_f32_e32 v224, v78, v224
	v_add_f32_e32 v225, v79, v225
	s_waitcnt lgkmcnt(14)
	v_mfma_f32_32x32x16_bf16 v[188:203], v[242:245], v[124:127], v[188:203]
	ds_read_b64 v[242:243], v185 offset:39456
	ds_read_b64 v[244:245], v185 offset:39472
	v_cvt_pk_bf16_f32 v68, v72, v73
	v_cvt_pk_bf16_f32 v69, v74, v75
	v_cvt_pk_bf16_f32 v70, v76, v77
	v_cvt_pk_bf16_f32 v71, v78, v79
	v_add_f32_e32 v224, v224, v225
	v_add_f32_e32 v180, v180, v224
	s_waitcnt lgkmcnt(14)
	v_mfma_f32_32x32x16_bf16 v[48:63], v[204:207], v[64:67], v[48:63]
	ds_read_b64 v[204:205], v185 offset:25664
	ds_read_b64 v[206:207], v185 offset:25680
	s_waitcnt lgkmcnt(14)
	v_mfma_f32_32x32x16_bf16 v[32:47], v[208:211], v[64:67], v[32:47]
	ds_read_b64 v[208:209], v185 offset:30272
	ds_read_b64 v[210:211], v185 offset:30288
	v_sub_f32_e32 v186, v188, v179
	v_exp_f32_e32 v188, v186
	v_sub_f32_e32 v187, v189, v179
	v_exp_f32_e32 v189, v187
	v_sub_f32_e32 v186, v190, v179
	v_exp_f32_e32 v190, v186
	s_waitcnt lgkmcnt(14)
	v_mfma_f32_32x32x16_bf16 v[16:31], v[212:215], v[64:67], v[16:31]
	ds_read_b64 v[212:213], v185 offset:34880
	ds_read_b64 v[214:215], v185 offset:34896
	v_add_f32_e32 v226, v188, v226
	v_sub_f32_e32 v187, v191, v179
	v_exp_f32_e32 v191, v187
	v_add_f32_e32 v183, v189, v183
	v_sub_f32_e32 v186, v192, v179
	v_exp_f32_e32 v192, v186
	s_waitcnt lgkmcnt(14)
	v_mfma_f32_32x32x16_bf16 v[0:15], v[216:219], v[64:67], v[0:15]
	ds_read_b64 v[216:217], v185 offset:39488
	ds_read_b64 v[218:219], v185 offset:39504
	v_add_f32_e32 v226, v190, v226
	v_sub_f32_e32 v187, v193, v179
	v_exp_f32_e32 v193, v187
	v_add_f32_e32 v183, v191, v183
	v_sub_f32_e32 v186, v194, v179
	v_exp_f32_e32 v194, v186
	s_waitcnt lgkmcnt(14)
	v_mfma_f32_32x32x16_bf16 v[48:63], v[220:223], v[68:71], v[48:63]
	ds_read_b64 v[220:221], v185 offset:25696
	ds_read_b64 v[222:223], v185 offset:25712
	v_add_f32_e32 v226, v192, v226
	v_sub_f32_e32 v187, v195, v179
	v_exp_f32_e32 v195, v187
	v_add_f32_e32 v183, v193, v183
	v_add_f32_e32 v226, v194, v226
	v_add_f32_e32 v183, v195, v183
	s_waitcnt lgkmcnt(14)
	v_mfma_f32_32x32x16_bf16 v[32:47], v[228:231], v[68:71], v[32:47]
	ds_read_b64 v[228:229], v185 offset:30304
	ds_read_b64 v[230:231], v185 offset:30320
	v_cvt_pk_bf16_f32 v188, v188, v189
	v_cvt_pk_bf16_f32 v189, v190, v191
	v_cvt_pk_bf16_f32 v190, v192, v193
	v_cvt_pk_bf16_f32 v191, v194, v195
	s_waitcnt lgkmcnt(14)
	v_mfma_f32_32x32x16_bf16 v[16:31], v[232:235], v[68:71], v[16:31]
	ds_read_b64 v[232:233], v185 offset:34912
	ds_read_b64 v[234:235], v185 offset:34928
	v_sub_f32_e32 v186, v196, v179
	v_exp_f32_e32 v196, v186
	v_sub_f32_e32 v187, v197, v179
	v_exp_f32_e32 v197, v187
	v_sub_f32_e32 v186, v198, v179
	v_exp_f32_e32 v198, v186
	s_waitcnt lgkmcnt(14)
	v_mfma_f32_32x32x16_bf16 v[0:15], v[242:245], v[68:71], v[0:15]
	ds_read_b64 v[242:243], v185 offset:39520
	ds_read_b64 v[244:245], v185 offset:39536
	v_add_f32_e32 v226, v196, v226
	v_sub_f32_e32 v187, v199, v179
	v_exp_f32_e32 v199, v187
	v_add_f32_e32 v183, v197, v183
	v_sub_f32_e32 v186, v200, v179
	v_exp_f32_e32 v200, v186
	s_waitcnt lgkmcnt(14)
	v_mfma_f32_32x32x16_bf16 v[48:63], v[204:207], v[188:191], v[48:63]
	v_add_f32_e32 v226, v198, v226
	v_sub_f32_e32 v187, v201, v179
	v_exp_f32_e32 v201, v187
	v_add_f32_e32 v183, v199, v183
	v_sub_f32_e32 v186, v202, v179
	v_exp_f32_e32 v202, v186
	s_waitcnt lgkmcnt(12)
	v_mfma_f32_32x32x16_bf16 v[32:47], v[208:211], v[188:191], v[32:47]
	v_add_f32_e32 v226, v200, v226
	v_sub_f32_e32 v187, v203, v179
	v_exp_f32_e32 v203, v187
	v_add_f32_e32 v183, v201, v183
	v_add_f32_e32 v226, v202, v226
	v_add_f32_e32 v183, v203, v183
	s_waitcnt lgkmcnt(10)
	v_mfma_f32_32x32x16_bf16 v[16:31], v[212:215], v[188:191], v[16:31]
	v_cvt_pk_bf16_f32 v192, v196, v197
	v_cvt_pk_bf16_f32 v193, v198, v199
	v_cvt_pk_bf16_f32 v194, v200, v201
	v_cvt_pk_bf16_f32 v195, v202, v203
	v_add_f32_e32 v226, v226, v183
	v_add_f32_e32 v180, v180, v226
	s_waitcnt lgkmcnt(8)
	v_mfma_f32_32x32x16_bf16 v[0:15], v[216:219], v[188:191], v[0:15]
	s_waitcnt lgkmcnt(6)
	v_mfma_f32_32x32x16_bf16 v[48:63], v[220:223], v[192:195], v[48:63]
	s_waitcnt lgkmcnt(4)
	v_mfma_f32_32x32x16_bf16 v[32:47], v[228:231], v[192:195], v[32:47]
	s_waitcnt lgkmcnt(2)
	v_mfma_f32_32x32x16_bf16 v[16:31], v[232:235], v[192:195], v[16:31]
	s_waitcnt lgkmcnt(0)
	v_mfma_f32_32x32x16_bf16 v[0:15], v[242:245], v[192:195], v[0:15]
	s_branch .LBB0_455
